# mLSTM chunk loop: fragment reads of the three matrix segments issued up front into unused registers with counted lgkmcnt waits (plus DPP gate scan, full-line GEMM staging)
# speedup vs baseline: 1.0082x; 1.0035x over previous
.LBB0_678:
	s_or_b64 exec, exec, s[4:5]
	ds_read_b128 v[84:87], v88
	ds_read_b128 v[80:83], v88 offset:32
	ds_read_b128 v[76:79], v88 offset:64
	ds_read_b128 v[72:75], v88 offset:96
	ds_read_b128 v[68:71], v88 offset:128
	ds_read_b128 v[64:67], v88 offset:160
	ds_read_b128 v[60:63], v88 offset:192
	ds_read_b128 v[56:59], v88 offset:224
	v_cndmask_b32_e64 v0, 0, 1, s[92:93]
	v_cmp_ne_u32_e64 s[56:57], 1, v0
	s_andn2_b64 vcc, exec, s[92:93]
	s_mov_b64 s[4:5], -1
	s_cbranch_vccnz .LBB0_680
	s_waitcnt lgkmcnt(8)
	ds_read_b128 v[0:3], v157 offset:51200
	ds_read_b128 v[174:177], v157 offset:51232
	ds_read_b128 v[180:183], v157 offset:51264
	ds_read_b128 v[184:187], v157 offset:51296
	ds_read_b128 v[188:191], v157 offset:51328
	ds_read_b128 v[192:195], v157 offset:51360
	ds_read_b128 v[196:199], v157 offset:51392
	s_mov_b64 s[4:5], 0
	s_waitcnt lgkmcnt(6)
	v_mfma_f32_32x32x16_bf16 v[0:15], v[0:3], v[84:87], 0
	ds_read_b128 v[200:203], v157 offset:51424
	ds_read_b32 v100, v139 offset:256
	s_waitcnt lgkmcnt(7)
	v_mfma_f32_32x32x16_bf16 v[0:15], v[174:177], v[80:83], v[0:15]
	s_waitcnt lgkmcnt(6)
	v_mfma_f32_32x32x16_bf16 v[0:15], v[180:183], v[76:79], v[0:15]
	s_waitcnt lgkmcnt(5)
	v_mfma_f32_32x32x16_bf16 v[0:15], v[184:187], v[72:75], v[0:15]
	s_waitcnt lgkmcnt(4)
	v_mfma_f32_32x32x16_bf16 v[0:15], v[188:191], v[68:71], v[0:15]
	s_waitcnt lgkmcnt(3)
	v_mfma_f32_32x32x16_bf16 v[0:15], v[192:195], v[64:67], v[0:15]
	s_waitcnt lgkmcnt(2)
	v_mfma_f32_32x32x16_bf16 v[0:15], v[196:199], v[60:63], v[0:15]
	s_waitcnt lgkmcnt(1)
	v_mfma_f32_32x32x16_bf16 v[0:15], v[200:203], v[56:59], v[0:15]
	s_waitcnt lgkmcnt(0)
	s_nop 10
	v_pk_mul_f32 v[14:15], v[100:101], v[14:15] op_sel_hi:[0,1]
	v_pk_mul_f32 v[12:13], v[100:101], v[12:13] op_sel_hi:[0,1]
	v_pk_mul_f32 v[10:11], v[100:101], v[10:11] op_sel_hi:[0,1]
	v_pk_mul_f32 v[8:9], v[100:101], v[8:9] op_sel_hi:[0,1]
	v_pk_mul_f32 v[6:7], v[100:101], v[6:7] op_sel_hi:[0,1]
	v_pk_mul_f32 v[4:5], v[100:101], v[4:5] op_sel_hi:[0,1]
	v_pk_mul_f32 v[2:3], v[100:101], v[2:3] op_sel_hi:[0,1]
	v_pk_mul_f32 v[0:1], v[100:101], v[0:1] op_sel_hi:[0,1]
.LBB0_680:
	s_andn2_b64 vcc, exec, s[4:5]
	s_cbranch_vccnz .LBB0_684
	s_waitcnt lgkmcnt(8)
	ds_read_b128 v[0:3], v158 offset:17408
	ds_read_b128 v[180:183], v159 offset:17408
	ds_read_b128 v[184:187], v160 offset:17408
	ds_read_b128 v[188:191], v161 offset:17408
	ds_read_b128 v[192:195], v162 offset:17408
	ds_read_b128 v[196:199], v163 offset:17408
	ds_read_b128 v[200:203], v164 offset:17408
	s_waitcnt lgkmcnt(6)
	v_mfma_f32_32x32x16_bf16 v[0:15], v[0:3], v[84:87], 0
	ds_read_b128 v[204:207], v165 offset:17408
	ds_read_b32 v208, v139
	s_waitcnt lgkmcnt(7)
	v_mfma_f32_32x32x16_bf16 v[0:15], v[180:183], v[80:83], v[0:15]
	s_waitcnt lgkmcnt(6)
	v_mfma_f32_32x32x16_bf16 v[0:15], v[184:187], v[76:79], v[0:15]
	s_waitcnt lgkmcnt(5)
	v_mfma_f32_32x32x16_bf16 v[0:15], v[188:191], v[72:75], v[0:15]
	s_waitcnt lgkmcnt(4)
	v_mfma_f32_32x32x16_bf16 v[0:15], v[192:195], v[68:71], v[0:15]
	s_waitcnt lgkmcnt(3)
	v_mfma_f32_32x32x16_bf16 v[0:15], v[196:199], v[64:67], v[0:15]
	s_waitcnt lgkmcnt(2)
	v_mfma_f32_32x32x16_bf16 v[0:15], v[200:203], v[60:63], v[0:15]
	s_waitcnt lgkmcnt(1)
	v_mfma_f32_32x32x16_bf16 v[0:15], v[204:207], v[56:59], v[0:15]
	s_waitcnt lgkmcnt(0)
	s_nop 9
	v_mov_b32_e32 v58, v208
	v_mul_f32_e32 v56, v58, v0
	v_cndmask_b32_e64 v56, v56, 0, s[22:23]
	v_mul_f32_e32 v59, v58, v1
	v_add_f32_e32 v57, 0, v56
	v_cndmask_b32_e64 v59, 0, v59, s[24:25]
	v_mul_f32_e32 v60, v58, v2
	v_add_f32_e32 v57, v59, v57
	v_cndmask_b32_e64 v60, v60, 0, s[26:27]
	v_mul_f32_e32 v61, v58, v3
	v_add_f32_e32 v57, v60, v57
	v_cndmask_b32_e64 v61, v61, 0, s[28:29]
	v_cvt_pk_bf16_f32 v56, v56, v59
	v_add_f32_e32 v62, v61, v57
	v_cvt_pk_bf16_f32 v57, v60, v61
	ds_write_b64 v166, v[56:57] offset:41984
	v_mul_f32_e32 v56, v58, v4
	v_cndmask_b32_e64 v56, v56, 0, s[30:31]
	v_mul_f32_e32 v59, v58, v5
	v_add_f32_e32 v57, v56, v62
	v_cndmask_b32_e64 v59, v59, 0, s[34:35]
	v_mul_f32_e32 v60, v58, v6
	v_add_f32_e32 v57, v59, v57
	v_cndmask_b32_e64 v60, v60, 0, s[36:37]
	v_mul_f32_e32 v61, v58, v7
	v_add_f32_e32 v57, v60, v57
	v_cndmask_b32_e64 v61, v61, 0, s[38:39]
	v_cvt_pk_bf16_f32 v56, v56, v59
	v_add_f32_e32 v62, v61, v57
	v_cvt_pk_bf16_f32 v57, v60, v61
	ds_write_b64 v166, v[56:57] offset:42000
	v_mul_f32_e32 v56, v58, v8
	v_cndmask_b32_e64 v56, v56, 0, s[40:41]
	v_mul_f32_e32 v59, v58, v9
	v_add_f32_e32 v57, v56, v62
	v_cndmask_b32_e64 v59, v59, 0, s[42:43]
	v_mul_f32_e32 v60, v58, v10
	v_add_f32_e32 v57, v59, v57
	v_cndmask_b32_e64 v60, v60, 0, s[44:45]
	v_mul_f32_e32 v61, v58, v11
	v_add_f32_e32 v57, v60, v57
	v_cndmask_b32_e64 v61, v61, 0, s[46:47]
	v_cvt_pk_bf16_f32 v56, v56, v59
	v_add_f32_e32 v62, v61, v57
	v_cvt_pk_bf16_f32 v57, v60, v61
	ds_write_b64 v166, v[56:57] offset:42016
	v_mul_f32_e32 v56, v58, v12
	v_cndmask_b32_e64 v57, v56, 0, s[48:49]
	v_mul_f32_e32 v59, v58, v13
	v_add_f32_e32 v56, v57, v62
	v_cndmask_b32_e64 v59, v59, 0, s[50:51]
	v_mul_f32_e32 v60, v58, v14
	v_add_f32_e32 v56, v59, v56
	v_cndmask_b32_e64 v60, v60, 0, s[52:53]
	v_mul_f32_e32 v58, v58, v15
	v_add_f32_e32 v56, v60, v56
	v_cndmask_b32_e64 v61, v58, 0, s[54:55]
	v_add_f32_e32 v56, v61, v56
	v_cvt_pk_bf16_f32 v58, v57, v59
	ds_bpermute_b32 v57, v140, v56
	v_cvt_pk_bf16_f32 v59, v60, v61
	ds_write_b64 v166, v[58:59] offset:42032
	s_and_saveexec_b64 s[4:5], s[20:21]
	s_cbranch_execz .LBB0_683
	s_waitcnt lgkmcnt(1)
	v_add_f32_e32 v56, v56, v57
	v_add_u32_e32 v57, s58, v136
	ds_write_b32 v57, v56

.LBB0_684:
	s_waitcnt lgkmcnt(0)
	s_barrier
	s_and_b64 vcc, exec, s[56:57]
	v_add_u32_e32 v174, s59, v141
	v_lshl_add_u64 v[100:101], v[96:97], 0, s[94:95]
	s_cbranch_vccnz .LBB0_686
	s_waitcnt lgkmcnt(0)
	ds_read_b64_tr_b16 v[56:57], v174 offset:33792
	ds_read_b64_tr_b16 v[58:59], v174 offset:34048
	ds_read_b128 v[60:63], v167 offset:41984
	ds_read_b128 v[64:67], v167 offset:42016
	ds_read_b64_tr_b16 v[180:181], v174 offset:35840
	ds_read_b64_tr_b16 v[182:183], v174 offset:36096
	ds_read_b64_tr_b16 v[184:185], v174 offset:37888
	ds_read_b64_tr_b16 v[186:187], v174 offset:38144
	ds_read_b128 v[188:191], v167 offset:42048
	ds_read_b64_tr_b16 v[192:193], v174 offset:39936
	ds_read_b64_tr_b16 v[194:195], v174 offset:40192
	ds_read_b128 v[196:199], v167 offset:42080
	ds_read_b32 v204, v142
	ds_read_b32 v205, v143
	ds_read_b32 v206, v136
	s_waitcnt lgkmcnt(12)
	v_mfma_f32_32x32x16_bf16 v[0:15], v[56:59], v[60:63], v[0:15]
	s_waitcnt lgkmcnt(9)
	v_mfma_f32_32x32x16_bf16 v[0:15], v[180:183], v[64:67], v[0:15]
	ds_read_b32 v207, v144
	ds_read_b32 v208, v139 offset:512
	s_waitcnt lgkmcnt(8)
	v_mfma_f32_32x32x16_bf16 v[0:15], v[184:187], v[188:191], v[0:15]
	s_waitcnt lgkmcnt(5)
	v_mfma_f32_32x32x16_bf16 v[0:15], v[192:195], v[196:199], v[0:15]
	s_waitcnt lgkmcnt(2)
	v_mov_b32_e32 v58, v206
	v_fmac_f32_e32 v58, v204, v205
	s_waitcnt lgkmcnt(1)
	v_add_f32_e32 v56, v58, v207
	s_waitcnt lgkmcnt(0)
	v_max_f32_e32 v57, v208, v208
	v_max_f32_e64 v56, |v56|, v57
	v_div_scale_f32 v57, s[4:5], v56, v56, 1.0
	v_rcp_f32_e32 v58, v57
	s_mov_b32 s4, 0x1a000000
	v_fma_f32 v59, -v57, v58, 1.0
	v_fmac_f32_e32 v58, v59, v58
	v_div_scale_f32 v59, vcc, 1.0, v56, 1.0
	v_mul_f32_e32 v60, v59, v58
	v_fma_f32 v61, -v57, v60, v59
	v_fmac_f32_e32 v60, v61, v58
	v_fma_f32 v57, -v57, v60, v59
	v_div_fmas_f32 v57, v57, v58, v60
	v_div_fixup_f32 v56, v57, v56, 1.0
	v_mul_f32_e32 v0, v0, v56
	v_mul_f32_e32 v1, v1, v56
	v_cvt_pk_bf16_f32 v0, v0, v1
	v_mul_f32_e32 v1, v2, v56
	v_mul_f32_e32 v2, v3, v56
	v_cvt_pk_bf16_f32 v1, v1, v2
	v_add_co_u32_e32 v2, vcc, s4, v100
	s_nop 1
	v_addc_co_u32_e32 v3, vcc, 0, v101, vcc
	global_store_dwordx2 v[2:3], v[0:1], off
	v_mul_f32_e32 v0, v4, v56
	v_mul_f32_e32 v1, v5, v56
	v_cvt_pk_bf16_f32 v0, v0, v1
	v_mul_f32_e32 v1, v6, v56
	v_mul_f32_e32 v4, v7, v56
	v_cvt_pk_bf16_f32 v1, v1, v4
	global_store_dwordx2 v[2:3], v[0:1], off offset:16
	v_mul_f32_e32 v0, v8, v56
	v_mul_f32_e32 v1, v9, v56
	v_cvt_pk_bf16_f32 v0, v0, v1
	v_mul_f32_e32 v1, v10, v56
	v_mul_f32_e32 v4, v11, v56
	v_cvt_pk_bf16_f32 v1, v1, v4
	global_store_dwordx2 v[2:3], v[0:1], off offset:32
	v_mul_f32_e32 v0, v12, v56
	v_mul_f32_e32 v1, v13, v56
	v_cvt_pk_bf16_f32 v0, v0, v1
	v_mul_f32_e32 v1, v14, v56
	v_mul_f32_e32 v4, v15, v56
	v_cvt_pk_bf16_f32 v1, v1, v4
	global_store_dwordx2 v[2:3], v[0:1], off offset:48
